# barrier release fan-out trimmed from 16 to 8 counter copies (32 pollers per copy)
# speedup vs baseline: 1.0001x; 1.0001x over previous
.LBB0_122:
	s_or_b64 exec, exec, s[10:11]
	v_cvt_f32_u32_e32 v4, v2
	s_waitcnt vmcnt(0)
	v_readfirstlane_b32 s2, v3
	v_sub_u32_e32 v3, 0, v2
	v_rcp_iflag_f32_e32 v4, v4
	v_add_u32_e32 v5, s2, v1
	v_mul_f32_e32 v4, 0x4f7ffffe, v4
	v_cvt_u32_f32_e32 v4, v4
	v_mul_lo_u32 v1, v3, v4
	v_mul_hi_u32 v1, v4, v1
	v_add_u32_e32 v1, v4, v1
	v_mul_hi_u32 v1, v5, v1
	v_mul_lo_u32 v3, v1, v2
	v_sub_u32_e32 v3, v5, v3
	v_add_u32_e32 v4, 1, v1
	v_cmp_ge_u32_e32 vcc, v3, v2
	s_nop 1
	v_cndmask_b32_e32 v1, v1, v4, vcc
	v_sub_u32_e32 v4, v3, v2
	v_cndmask_b32_e32 v3, v3, v4, vcc
	v_add_u32_e32 v4, 1, v1
	v_cmp_ge_u32_e32 vcc, v3, v2
	v_add_u32_e32 v3, 1, v5
	s_nop 0
	v_cndmask_b32_e32 v1, v1, v4, vcc
	v_mul_lo_u32 v4, v2, v1
	v_add_u32_e32 v2, v4, v2
	s_waitcnt lgkmcnt(0)
	v_add_u32_e32 v4, 1, v1
	v_mul_lo_u32 v4, v4, v0
	v_readlane_b32 s14, v252, 2
	v_readlane_b32 s15, v252, 3
	s_add_u32 s14, s14, 0x2400
	s_addc_u32 s15, s15, 0
	v_mov_b32_e32 v6, 0
	v_cmp_ne_u32_e32 vcc, v3, v2
	s_cbranch_vccnz .Lxb_pf_0
	buffer_wbl2 sc1
	s_waitcnt vmcnt(0)
	v_mov_b32_e32 v5, 1
	global_atomic_add v6, v5, s[14:15]
	global_atomic_add v6, v5, s[14:15] offset:256
	global_atomic_add v6, v5, s[14:15] offset:512
	global_atomic_add v6, v5, s[14:15] offset:768
	global_atomic_add v6, v5, s[14:15] offset:1024
	global_atomic_add v6, v5, s[14:15] offset:1280
	global_atomic_add v6, v5, s[14:15] offset:1536
	global_atomic_add v6, v5, s[14:15] offset:1792
	s_branch .Lxb_wait_0

.Lxb_wait_0:
	buffer_inv sc1
	v_readlane_b32 s16, v252, 5
	s_nop 3
	s_and_b32 s16, s16, 7
	s_lshl_b32 s16, s16, 8
	s_add_u32 s14, s14, s16
	s_addc_u32 s15, s15, 0
	s_mov_b32 s16, 0
